# attention phases P4/P5 (FoX, indexer, DSA): one static s_setprio 1 for waves 4-7 at phase entry, reset at P6
# baseline (speedup 1.0000x reference)
; #define LAS __attribute__((address_space(3)))
; __device__ __forceinline__ ArgsP get_args() { unsigned long long p = (unsigned long long)__builtin_amdgcn_kernarg_segment_ptr(); asm volatile("" : "+s"(p)); return (ArgsP)p; }
; __device__ __forceinline__ int q_grab(Frame& F, unsigned* head, int& par) {
;     if (F.tid == 0) F.MISC[32 + par] = atomicAdd(head, 1u);
; __global__ void __launch_bounds__(NWAVES * 64, 2) mk_fwd(Args args) {
;     ...
;     if (IN(4)) { a = get_args();
;         if (MK_DBG & 8) { for (int u = 135168 / 4 + F.tid; u < LDS_BYTES / 4; u += NWAVES * 64) ((LAS unsigned*)F.lds)[u] = 0u; __syncthreads(); }
;         if (MK_DBG & 16) { for (int q = 0; q < 64; ++q) __builtin_amdgcn_s_sleep(64); }
;         if (MK_ATTN & 1) {
;             const float* biasK = (const float*)(a->ws + WS_BIASK);
;             float thr;
;             { const float* gq = (const float*)a->in[I_GQB]; const float* gk = (const float*)a->in[I_GKB];
;               float mq = fmaxf(fabsf(gq[F.lane]), fabsf(gq[F.lane + 64])), mk_ = fmaxf(fabsf(gk[F.lane]), fabsf(gk[F.lane + 64]));
; #pragma unroll
;               for (int o = 1; o < 64; o <<= 1) { mq = fmaxf(mq, __shfl_xor(mq, o)); mk_ = fmaxf(mk_, __shfl_xor(mk_, o)); }
;               thr = 2.0f * 11.313708499f * 1.03f * mq * mk_ + 96.0f; }
.LBB0_512:
	v_readlane_b32 s2, v254, 11
	v_readlane_b32 s3, v254, 12
	s_cmp_lt_i32 s2, 5
	s_cselect_b64 s[2:3], -1, 0
	s_and_b64 s[0:1], s[2:3], s[0:1]
	v_writelane_b32 v254, s0, 15
	s_andn2_b64 vcc, exec, s[0:1]
	s_nop 0
	v_writelane_b32 v254, s1, 16
	v_writelane_b32 v254, s74, 17
	s_cbranch_vccnz .LBB0_1158
	v_readlane_b32 s98, v254, 10
	s_cmp_lt_u32 s98, 4
	s_cbranch_scc1 .Lsp_attn
	s_setprio 1
.Lsp_attn:
	s_mov_b64 s[4:5], s[56:57]
	s_load_dwordx4 s[0:3], s[4:5], 0x68
	v_lshlrev_b32_e32 v1, 2, v232
	v_writelane_b32 v254, s4, 18
	s_waitcnt lgkmcnt(0)
	global_load_dword v2, v1, s[0:1] offset:256
	global_load_dword v3, v1, s[0:1]
	global_load_dword v4, v1, s[2:3] offset:256
	global_load_dword v5, v1, s[2:3]
	v_mbcnt_lo_u32_b32 v1, -1, 0
	v_mbcnt_hi_u32_b32 v6, -1, v1
	v_and_b32_e32 v1, 64, v6
	v_xor_b32_e32 v7, 1, v6
	v_add_u32_e32 v13, 64, v1
	v_cmp_lt_i32_e32 vcc, v7, v13
	v_xor_b32_e32 v8, 2, v6
	v_xor_b32_e32 v9, 4, v6
	v_cndmask_b32_e32 v1, v6, v7, vcc
	v_lshlrev_b32_e32 v1, 2, v1
	v_cmp_lt_i32_e32 vcc, v8, v13
	v_xor_b32_e32 v10, 8, v6
	v_xor_b32_e32 v11, 16, v6
	v_cndmask_b32_e32 v7, v6, v8, vcc
	v_lshlrev_b32_e32 v213, 2, v7
	v_cmp_lt_i32_e32 vcc, v9, v13
	s_load_dwordx2 s[84:85], s[4:5], 0xd0
	v_xor_b32_e32 v12, 32, v6
	v_cndmask_b32_e32 v7, v6, v9, vcc
	v_lshlrev_b32_e32 v253, 2, v7
	v_cmp_lt_i32_e32 vcc, v10, v13
	s_waitcnt lgkmcnt(0)
	s_add_u32 s0, s84, 0x8000
	v_writelane_b32 v254, s5, 19
	v_cndmask_b32_e32 v7, v6, v10, vcc
	v_lshlrev_b32_e32 v210, 2, v7
	v_cmp_lt_i32_e32 vcc, v11, v13
	s_addc_u32 s1, s85, 0
	v_writelane_b32 v254, s0, 20
	v_cndmask_b32_e32 v7, v6, v11, vcc
	v_lshlrev_b32_e32 v7, 2, v7
	v_cmp_lt_i32_e32 vcc, v12, v13
	v_writelane_b32 v254, s1, 21
	s_waitcnt vmcnt(0)
	v_max_f32_e64 v2, |v2|, |v2|
	v_max_f32_e64 v3, |v3|, |v3|
	v_max_f32_e64 v4, |v4|, |v4|
	v_max_f32_e64 v5, |v5|, |v5|
	v_max_f32_e32 v2, v3, v2
	v_max_f32_e32 v3, v5, v4
	s_nop 1
	v_mov_b32_dpp v4, v2 quad_perm:[1,0,3,2] row_mask:0xf bank_mask:0xf
	s_nop 1
	v_mov_b32_dpp v5, v3 quad_perm:[1,0,3,2] row_mask:0xf bank_mask:0xf
	v_cndmask_b32_e32 v6, v6, v12, vcc
	v_lshlrev_b32_e32 v6, 2, v6
	s_waitcnt lgkmcnt(1)
	v_max_f32_e32 v4, v4, v4
	s_waitcnt lgkmcnt(0)
	v_max_f32_e32 v5, v5, v5
	v_max_f32_e32 v2, v2, v4
	v_max_f32_e32 v3, v3, v5
	ds_bpermute_b32 v4, v213, v2
	ds_bpermute_b32 v5, v213, v3
	s_waitcnt lgkmcnt(1)
	v_max_f32_e32 v4, v4, v4
	s_waitcnt lgkmcnt(0)
	v_max_f32_e32 v5, v5, v5
	v_max_f32_e32 v2, v2, v4
	v_max_f32_e32 v3, v3, v5
	ds_bpermute_b32 v4, v253, v2
	ds_bpermute_b32 v5, v253, v3
	s_waitcnt lgkmcnt(1)
	v_max_f32_e32 v4, v4, v4
	s_waitcnt lgkmcnt(0)
	v_max_f32_e32 v5, v5, v5
	v_max_f32_e32 v2, v2, v4
	v_max_f32_e32 v3, v3, v5
	ds_bpermute_b32 v4, v210, v2
	ds_bpermute_b32 v5, v210, v3
	s_waitcnt lgkmcnt(1)
	v_max_f32_e32 v4, v4, v4
	s_waitcnt lgkmcnt(0)
	v_max_f32_e32 v5, v5, v5
	v_max_f32_e32 v2, v2, v4
	v_max_f32_e32 v4, v3, v5
	ds_bpermute_b32 v3, v7, v2
	ds_bpermute_b32 v5, v7, v4
	s_waitcnt lgkmcnt(1)
	v_max_f32_e32 v3, v3, v3
	s_waitcnt lgkmcnt(0)
	v_max_f32_e32 v5, v5, v5
	v_max_f32_e32 v3, v2, v3
	v_max_f32_e32 v2, v4, v5
	ds_bpermute_b32 v5, v6, v3
	ds_bpermute_b32 v4, v6, v2
	s_mov_b64 s[0:1], exec
	v_readlane_b32 s2, v254, 8
	v_readlane_b32 s3, v254, 9
	s_and_b64 s[2:3], s[0:1], s[2:3]
	s_mov_b64 exec, s[2:3]
	s_cbranch_execz .LBB0_517
	s_mov_b64 s[4:5], exec
	v_mbcnt_lo_u32_b32 v6, s4, 0
	v_mbcnt_hi_u32_b32 v6, s5, v6
	v_cmp_eq_u32_e32 vcc, 0, v6
	s_and_saveexec_b64 s[2:3], vcc
	s_cbranch_execz .LBB0_516
	s_bcnt1_i32_b64 s4, s[4:5]
	v_mov_b32_e32 v8, s4
	v_readlane_b32 s4, v254, 20
	v_mov_b32_e32 v7, 0
	v_readlane_b32 s5, v254, 21
	s_nop 4
	global_atomic_add v7, v7, v8, s[4:5] sc0

;     __host__ __device__ bool next(int i, Unit& u) const { const bool ok = StaticOrder::next(i >> 1, u); u.z = i & 1; return ok; }
; __device__ __forceinline__ ArgsP get_args() { unsigned long long p = (unsigned long long)__builtin_amdgcn_kernarg_segment_ptr(); asm volatile("" : "+s"(p)); return (ArgsP)p; }
;     __host__ __device__ bool next(int i, Unit& u) const {
;         const long L = (long)i * G + c; if (L >= nwg) return false;
;         int wgid = (int)L; { const int q = nwg / NXCD, r = nwg % NXCD, xcd = wgid % NXCD, off = wgid / NXCD; wgid = (xcd < r ? xcd * (q + 1) : r * (q + 1) + (xcd - r) * q) + off; }
; __global__ void __launch_bounds__(NWAVES * 64, 2) mk_fwd(Args args) {
;     ...
;     if (IN(6)) { a = get_args();
;         pg8::Gemm g{(MK_ATTN & 8) ? RD + (size_t)M * 2048 : RA + (size_t)M * 2048, (const bf16_t*)(a->ws + WS_WUPA), (MK_ATTN & 8) ? RD + (size_t)2 * M * 2048 : RD, (const bf16_t*)(a->ws + WS_WUPB), M, DM, 2048}; pg8::DualOrder S; S.init(M, DM, F.G, (int)blockIdx.x);
;         pg8::EpiMerge E{RG, (MK_ATTN & 8) ? RA : RD + (size_t)M * 2048, RB};
;         pg8::gemm_phase<pg8::EpiMerge, pg8::DualOrder>(F.lds, g, S, E);
.LBB0_1440:
	s_setprio 0
	v_readlane_b32 s2, v254, 11
	v_readlane_b32 s3, v254, 12
	s_cmp_lt_i32 s2, 7
	s_cselect_b64 s[2:3], -1, 0
	s_and_b64 s[4:5], s[2:3], s[0:1]
	s_andn2_b64 vcc, exec, s[4:5]
	s_mov_b32 s78, s54
	s_cbranch_vccnz .LBB0_1565
	s_mov_b64 s[0:1], s[56:57]
	s_load_dwordx2 s[6:7], s[0:1], 0xd0
	s_cmpk_lt_i32 s74, 0x400
	s_cselect_b64 s[0:1], -1, 0
	s_cmpk_gt_i32 s74, 0x3ff
	v_readfirstlane_b32 s14, v0
	s_cbranch_scc1 .LBB0_1447
	s_ashr_i32 s2, s74, 31
	s_lshr_b32 s2, s2, 29
	s_add_i32 s8, s74, s2
	s_and_b32 s2, s8, -8
	s_sub_i32 s9, s74, s2
	s_cmp_gt_i32 s9, -1
	s_cbranch_scc0 .LBB0_1444
	s_lshl_b32 s10, s9, 7
	s_cbranch_execz .LBB0_1445
	s_branch .LBB0_1446
